# P0 row copy (x -> bf16 + row sum of squares): hand-written loop, scalar row index and base, four rows of loads in flight with exact counted waits
# baseline (speedup 1.0000x reference)
.LBB0_120:
	s_or_b64 exec, exec, s[4:5]
	s_mov_b32 s0, 0x8000
	v_cmp_gt_i32_e32 vcc, s0, v18
	s_and_saveexec_b64 s[4:5], vcc
	s_cbranch_execz .LBB0_125
	v_mbcnt_hi_u32_b32 v3, -1, v254
	v_and_b32_e32 v5, 64, v3
	v_xor_b32_e32 v4, 1, v3
	v_add_u32_e32 v5, 64, v5
	v_cmp_lt_i32_e32 vcc, v4, v5
	s_mov_b64 s[0:1], 0x26b0000
	v_ashrrev_i32_e32 v21, 31, v20
	v_cndmask_b32_e32 v4, v3, v4, vcc
	v_lshlrev_b32_e32 v32, 2, v4
	v_xor_b32_e32 v4, 2, v3
	v_cmp_lt_i32_e32 vcc, v4, v5
	v_mov_b32_e32 v23, 0
	v_lshlrev_b64 v[26:27], 2, v[20:21]
	v_cndmask_b32_e32 v4, v3, v4, vcc
	v_lshlrev_b32_e32 v33, 2, v4
	v_xor_b32_e32 v4, 4, v3
	v_cmp_lt_i32_e32 vcc, v4, v5
	v_lshlrev_b64 v[30:31], 11, v[20:21]
	s_mov_b64 s[6:7], 0
	v_cndmask_b32_e32 v4, v3, v4, vcc
	v_lshlrev_b32_e32 v34, 2, v4
	v_xor_b32_e32 v4, 8, v3
	v_cmp_lt_i32_e32 vcc, v4, v5
	s_movk_i32 s8, 0x4000
	v_mov_b32_e32 v38, s53
	v_cndmask_b32_e32 v4, v3, v4, vcc
	v_lshlrev_b32_e32 v35, 2, v4
	v_xor_b32_e32 v4, 16, v3
	v_cmp_lt_i32_e32 vcc, v4, v5
	v_mov_b32_e32 v39, s54
	v_mov_b32_e32 v40, s52
	v_cndmask_b32_e32 v4, v3, v4, vcc
	v_lshlrev_b32_e32 v36, 2, v4
	v_xor_b32_e32 v4, 32, v3
	v_cmp_lt_i32_e32 vcc, v4, v5
	v_lshlrev_b32_e32 v22, 2, v2
	s_movk_i32 s9, 0x7fff
	v_cndmask_b32_e32 v3, v3, v4, vcc
	v_lshl_add_u64 v[4:5], v[18:19], 2, s[78:79]
	v_lshl_add_u64 v[24:25], v[4:5], 0, s[0:1]
	v_lshlrev_b64 v[4:5], 11, v[18:19]
	v_lshl_or_b32 v4, v1, 3, v4
	v_lshl_add_u64 v[4:5], s[76:77], 0, v[4:5]
	s_mov_b64 s[0:1], 0x4000000
	v_lshlrev_b32_e32 v37, 2, v3
	v_cmp_eq_u32_e32 vcc, 0, v1
	v_lshl_add_u64 v[28:29], v[4:5], 0, s[0:1]
	v_mov_b32_e32 v1, s55
	v_readfirstlane_b32 s98, v18
	v_readfirstlane_b32 s6, v20
	s_nop 0
	s_mov_b32 s99, s98
	s_min_i32 s7, s98, s9
	s_cmp_lt_i32 s7, s8
	s_cselect_b32 s0, s52, s54
	s_cselect_b32 s1, s53, s55
	s_and_b32 s7, s7, 0x3fff
	s_lshl_b32 s7, s7, 12
	s_add_u32 s0, s0, s7
	s_addc_u32 s1, s1, 0
	global_load_dwordx4 v[2:5], v22, s[0:1] nt
	global_load_dwordx4 v[6:9], v22, s[0:1] offset:1024 nt
	global_load_dwordx4 v[10:13], v22, s[0:1] offset:2048 nt
	global_load_dwordx4 v[14:17], v22, s[0:1] offset:3072 nt
	s_add_i32 s98, s98, s6
	s_min_i32 s7, s98, s9
	s_cmp_lt_i32 s7, s8
	s_cselect_b32 s0, s52, s54
	s_cselect_b32 s1, s53, s55
	s_and_b32 s7, s7, 0x3fff
	s_lshl_b32 s7, s7, 12
	s_add_u32 s0, s0, s7
	s_addc_u32 s1, s1, 0
	global_load_dwordx4 v[44:47], v22, s[0:1] nt
	global_load_dwordx4 v[48:51], v22, s[0:1] offset:1024 nt
	global_load_dwordx4 v[52:55], v22, s[0:1] offset:2048 nt
	global_load_dwordx4 v[56:59], v22, s[0:1] offset:3072 nt
	s_add_i32 s98, s98, s6
	s_min_i32 s7, s98, s9
	s_cmp_lt_i32 s7, s8
	s_cselect_b32 s0, s52, s54
	s_cselect_b32 s1, s53, s55
	s_and_b32 s7, s7, 0x3fff
	s_lshl_b32 s7, s7, 12
	s_add_u32 s0, s0, s7
	s_addc_u32 s1, s1, 0
	global_load_dwordx4 v[60:63], v22, s[0:1] nt
	global_load_dwordx4 v[64:67], v22, s[0:1] offset:1024 nt
	global_load_dwordx4 v[68:71], v22, s[0:1] offset:2048 nt
	global_load_dwordx4 v[72:75], v22, s[0:1] offset:3072 nt
	s_add_i32 s98, s98, s6
	s_min_i32 s7, s98, s9
	s_cmp_lt_i32 s7, s8
	s_cselect_b32 s0, s52, s54
	s_cselect_b32 s1, s53, s55
	s_and_b32 s7, s7, 0x3fff
	s_lshl_b32 s7, s7, 12
	s_add_u32 s0, s0, s7
	s_addc_u32 s1, s1, 0
	global_load_dwordx4 v[78:81], v22, s[0:1] nt
	global_load_dwordx4 v[82:85], v22, s[0:1] offset:1024 nt
	global_load_dwordx4 v[86:89], v22, s[0:1] offset:2048 nt
	global_load_dwordx4 v[90:93], v22, s[0:1] offset:3072 nt
	s_add_i32 s98, s98, s6
	s_waitcnt vmcnt(12)
	v_mul_f32_e32 v41, v3, v3
	v_mul_f32_e32 v42, v7, v7
	v_mul_f32_e32 v43, v11, v11
	v_mul_f32_e32 v76, v15, v15
	v_fmac_f32_e32 v41, v2, v2
	v_fmac_f32_e32 v42, v6, v6
	v_fmac_f32_e32 v43, v10, v10
	v_fmac_f32_e32 v76, v14, v14
	v_fmac_f32_e32 v41, v4, v4
	v_fmac_f32_e32 v42, v8, v8
	v_fmac_f32_e32 v43, v12, v12
	v_fmac_f32_e32 v76, v16, v16
	v_fmac_f32_e32 v41, v5, v5
	v_fmac_f32_e32 v42, v9, v9
	v_fmac_f32_e32 v43, v13, v13
	v_fmac_f32_e32 v76, v17, v17
	v_add_f32_e32 v41, v41, v42
	v_add_f32_e32 v41, v41, v43
	v_add_f32_e32 v41, v41, v76
	ds_bpermute_b32 v42, v32, v41
	v_cvt_pk_bf16_f32 v2, v2, v3
	v_cvt_pk_bf16_f32 v3, v4, v5
	global_store_dwordx2 v[28:29], v[2:3], off
	v_cvt_pk_bf16_f32 v6, v6, v7
	v_cvt_pk_bf16_f32 v7, v8, v9
	global_store_dwordx2 v[28:29], v[6:7], off offset:512
	v_cvt_pk_bf16_f32 v10, v10, v11
	v_cvt_pk_bf16_f32 v11, v12, v13
	global_store_dwordx2 v[28:29], v[10:11], off offset:1024
	v_cvt_pk_bf16_f32 v14, v14, v15
	v_cvt_pk_bf16_f32 v15, v16, v17
	global_store_dwordx2 v[28:29], v[14:15], off offset:1536
	v_lshl_add_u64 v[28:29], v[28:29], 0, v[30:31]
	s_waitcnt lgkmcnt(0)
	v_add_f32_e32 v41, v41, v42
	ds_bpermute_b32 v42, v33, v41
	s_waitcnt lgkmcnt(0)
	v_add_f32_e32 v41, v41, v42
	ds_bpermute_b32 v42, v34, v41
	s_waitcnt lgkmcnt(0)
	v_add_f32_e32 v41, v41, v42
	ds_bpermute_b32 v42, v35, v41
	s_waitcnt lgkmcnt(0)
	v_add_f32_e32 v41, v41, v42
	ds_bpermute_b32 v42, v36, v41
	s_waitcnt lgkmcnt(0)
	v_add_f32_e32 v41, v41, v42
	ds_bpermute_b32 v42, v37, v41
	s_waitcnt lgkmcnt(0)
	v_add_f32_e32 v41, v41, v42
	s_mov_b64 exec, 1
	global_store_dword v[24:25], v41, off
	s_mov_b64 exec, -1
	v_lshl_add_u64 v[24:25], v[24:25], 0, v[26:27]
	s_add_i32 s99, s99, s6
	s_cmp_gt_i32 s99, s9
	s_cbranch_scc1 .Lp0c_done
	s_min_i32 s7, s98, s9
	s_cmp_lt_i32 s7, s8
	s_cselect_b32 s0, s52, s54
	s_cselect_b32 s1, s53, s55
	s_and_b32 s7, s7, 0x3fff
	s_lshl_b32 s7, s7, 12
	s_add_u32 s0, s0, s7
	s_addc_u32 s1, s1, 0
	global_load_dwordx4 v[2:5], v22, s[0:1] nt
	global_load_dwordx4 v[6:9], v22, s[0:1] offset:1024 nt
	global_load_dwordx4 v[10:13], v22, s[0:1] offset:2048 nt
	global_load_dwordx4 v[14:17], v22, s[0:1] offset:3072 nt
	s_add_i32 s98, s98, s6
	s_waitcnt vmcnt(17)
	v_mul_f32_e32 v41, v45, v45
	v_mul_f32_e32 v42, v49, v49
	v_mul_f32_e32 v43, v53, v53
	v_mul_f32_e32 v76, v57, v57
	v_fmac_f32_e32 v41, v44, v44
	v_fmac_f32_e32 v42, v48, v48
	v_fmac_f32_e32 v43, v52, v52
	v_fmac_f32_e32 v76, v56, v56
	v_fmac_f32_e32 v41, v46, v46
	v_fmac_f32_e32 v42, v50, v50
	v_fmac_f32_e32 v43, v54, v54
	v_fmac_f32_e32 v76, v58, v58
	v_fmac_f32_e32 v41, v47, v47
	v_fmac_f32_e32 v42, v51, v51
	v_fmac_f32_e32 v43, v55, v55
	v_fmac_f32_e32 v76, v59, v59
	v_add_f32_e32 v41, v41, v42
	v_add_f32_e32 v41, v41, v43
	v_add_f32_e32 v41, v41, v76
	ds_bpermute_b32 v42, v32, v41
	v_cvt_pk_bf16_f32 v44, v44, v45
	v_cvt_pk_bf16_f32 v45, v46, v47
	global_store_dwordx2 v[28:29], v[44:45], off
	v_cvt_pk_bf16_f32 v48, v48, v49
	v_cvt_pk_bf16_f32 v49, v50, v51
	global_store_dwordx2 v[28:29], v[48:49], off offset:512
	v_cvt_pk_bf16_f32 v52, v52, v53
	v_cvt_pk_bf16_f32 v53, v54, v55
	global_store_dwordx2 v[28:29], v[52:53], off offset:1024
	v_cvt_pk_bf16_f32 v56, v56, v57
	v_cvt_pk_bf16_f32 v57, v58, v59
	global_store_dwordx2 v[28:29], v[56:57], off offset:1536
	v_lshl_add_u64 v[28:29], v[28:29], 0, v[30:31]
	s_waitcnt lgkmcnt(0)
	v_add_f32_e32 v41, v41, v42
	ds_bpermute_b32 v42, v33, v41
	s_waitcnt lgkmcnt(0)
	v_add_f32_e32 v41, v41, v42
	ds_bpermute_b32 v42, v34, v41
	s_waitcnt lgkmcnt(0)
	v_add_f32_e32 v41, v41, v42
	ds_bpermute_b32 v42, v35, v41
	s_waitcnt lgkmcnt(0)
	v_add_f32_e32 v41, v41, v42
	ds_bpermute_b32 v42, v36, v41
	s_waitcnt lgkmcnt(0)
	v_add_f32_e32 v41, v41, v42
	ds_bpermute_b32 v42, v37, v41
	s_waitcnt lgkmcnt(0)
	v_add_f32_e32 v41, v41, v42
	s_mov_b64 exec, 1
	global_store_dword v[24:25], v41, off
	s_mov_b64 exec, -1
	v_lshl_add_u64 v[24:25], v[24:25], 0, v[26:27]
	s_add_i32 s99, s99, s6
	s_cmp_gt_i32 s99, s9
	s_cbranch_scc1 .Lp0c_done
	s_min_i32 s7, s98, s9
	s_cmp_lt_i32 s7, s8
	s_cselect_b32 s0, s52, s54
	s_cselect_b32 s1, s53, s55
	s_and_b32 s7, s7, 0x3fff
	s_lshl_b32 s7, s7, 12
	s_add_u32 s0, s0, s7
	s_addc_u32 s1, s1, 0
	global_load_dwordx4 v[44:47], v22, s[0:1] nt
	global_load_dwordx4 v[48:51], v22, s[0:1] offset:1024 nt
	global_load_dwordx4 v[52:55], v22, s[0:1] offset:2048 nt
	global_load_dwordx4 v[56:59], v22, s[0:1] offset:3072 nt
	s_add_i32 s98, s98, s6
	s_waitcnt vmcnt(22)
	v_mul_f32_e32 v41, v61, v61
	v_mul_f32_e32 v42, v65, v65
	v_mul_f32_e32 v43, v69, v69
	v_mul_f32_e32 v76, v73, v73
	v_fmac_f32_e32 v41, v60, v60
	v_fmac_f32_e32 v42, v64, v64
	v_fmac_f32_e32 v43, v68, v68
	v_fmac_f32_e32 v76, v72, v72
	v_fmac_f32_e32 v41, v62, v62
	v_fmac_f32_e32 v42, v66, v66
	v_fmac_f32_e32 v43, v70, v70
	v_fmac_f32_e32 v76, v74, v74
	v_fmac_f32_e32 v41, v63, v63
	v_fmac_f32_e32 v42, v67, v67
	v_fmac_f32_e32 v43, v71, v71
	v_fmac_f32_e32 v76, v75, v75
	v_add_f32_e32 v41, v41, v42
	v_add_f32_e32 v41, v41, v43
	v_add_f32_e32 v41, v41, v76
	ds_bpermute_b32 v42, v32, v41
	v_cvt_pk_bf16_f32 v60, v60, v61
	v_cvt_pk_bf16_f32 v61, v62, v63
	global_store_dwordx2 v[28:29], v[60:61], off
	v_cvt_pk_bf16_f32 v64, v64, v65
	v_cvt_pk_bf16_f32 v65, v66, v67
	global_store_dwordx2 v[28:29], v[64:65], off offset:512
	v_cvt_pk_bf16_f32 v68, v68, v69
	v_cvt_pk_bf16_f32 v69, v70, v71
	global_store_dwordx2 v[28:29], v[68:69], off offset:1024
	v_cvt_pk_bf16_f32 v72, v72, v73
	v_cvt_pk_bf16_f32 v73, v74, v75
	global_store_dwordx2 v[28:29], v[72:73], off offset:1536
	v_lshl_add_u64 v[28:29], v[28:29], 0, v[30:31]
	s_waitcnt lgkmcnt(0)
	v_add_f32_e32 v41, v41, v42
	ds_bpermute_b32 v42, v33, v41
	s_waitcnt lgkmcnt(0)
	v_add_f32_e32 v41, v41, v42
	ds_bpermute_b32 v42, v34, v41
	s_waitcnt lgkmcnt(0)
	v_add_f32_e32 v41, v41, v42
	ds_bpermute_b32 v42, v35, v41
	s_waitcnt lgkmcnt(0)
	v_add_f32_e32 v41, v41, v42
	ds_bpermute_b32 v42, v36, v41
	s_waitcnt lgkmcnt(0)
	v_add_f32_e32 v41, v41, v42
	ds_bpermute_b32 v42, v37, v41
	s_waitcnt lgkmcnt(0)
	v_add_f32_e32 v41, v41, v42
	s_mov_b64 exec, 1
	global_store_dword v[24:25], v41, off
	s_mov_b64 exec, -1
	v_lshl_add_u64 v[24:25], v[24:25], 0, v[26:27]
	s_add_i32 s99, s99, s6
	s_cmp_gt_i32 s99, s9
	s_cbranch_scc1 .Lp0c_done
	s_min_i32 s7, s98, s9
	s_cmp_lt_i32 s7, s8
	s_cselect_b32 s0, s52, s54
	s_cselect_b32 s1, s53, s55
	s_and_b32 s7, s7, 0x3fff
	s_lshl_b32 s7, s7, 12
	s_add_u32 s0, s0, s7
	s_addc_u32 s1, s1, 0
	global_load_dwordx4 v[60:63], v22, s[0:1] nt
	global_load_dwordx4 v[64:67], v22, s[0:1] offset:1024 nt
	global_load_dwordx4 v[68:71], v22, s[0:1] offset:2048 nt
	global_load_dwordx4 v[72:75], v22, s[0:1] offset:3072 nt
	s_add_i32 s98, s98, s6
	s_waitcnt vmcnt(27)
	v_mul_f32_e32 v41, v79, v79
	v_mul_f32_e32 v42, v83, v83
	v_mul_f32_e32 v43, v87, v87
	v_mul_f32_e32 v76, v91, v91
	v_fmac_f32_e32 v41, v78, v78
	v_fmac_f32_e32 v42, v82, v82
	v_fmac_f32_e32 v43, v86, v86
	v_fmac_f32_e32 v76, v90, v90
	v_fmac_f32_e32 v41, v80, v80
	v_fmac_f32_e32 v42, v84, v84
	v_fmac_f32_e32 v43, v88, v88
	v_fmac_f32_e32 v76, v92, v92
	v_fmac_f32_e32 v41, v81, v81
	v_fmac_f32_e32 v42, v85, v85
	v_fmac_f32_e32 v43, v89, v89
	v_fmac_f32_e32 v76, v93, v93
	v_add_f32_e32 v41, v41, v42
	v_add_f32_e32 v41, v41, v43
	v_add_f32_e32 v41, v41, v76
	ds_bpermute_b32 v42, v32, v41
	v_cvt_pk_bf16_f32 v78, v78, v79
	v_cvt_pk_bf16_f32 v79, v80, v81
	global_store_dwordx2 v[28:29], v[78:79], off
	v_cvt_pk_bf16_f32 v82, v82, v83
	v_cvt_pk_bf16_f32 v83, v84, v85
	global_store_dwordx2 v[28:29], v[82:83], off offset:512
	v_cvt_pk_bf16_f32 v86, v86, v87
	v_cvt_pk_bf16_f32 v87, v88, v89
	global_store_dwordx2 v[28:29], v[86:87], off offset:1024
	v_cvt_pk_bf16_f32 v90, v90, v91
	v_cvt_pk_bf16_f32 v91, v92, v93
	global_store_dwordx2 v[28:29], v[90:91], off offset:1536
	v_lshl_add_u64 v[28:29], v[28:29], 0, v[30:31]
	s_waitcnt lgkmcnt(0)
	v_add_f32_e32 v41, v41, v42
	ds_bpermute_b32 v42, v33, v41
	s_waitcnt lgkmcnt(0)
	v_add_f32_e32 v41, v41, v42
	ds_bpermute_b32 v42, v34, v41
	s_waitcnt lgkmcnt(0)
	v_add_f32_e32 v41, v41, v42
	ds_bpermute_b32 v42, v35, v41
	s_waitcnt lgkmcnt(0)
	v_add_f32_e32 v41, v41, v42
	ds_bpermute_b32 v42, v36, v41
	s_waitcnt lgkmcnt(0)
	v_add_f32_e32 v41, v41, v42
	ds_bpermute_b32 v42, v37, v41
	s_waitcnt lgkmcnt(0)
	v_add_f32_e32 v41, v41, v42
	s_mov_b64 exec, 1
	global_store_dword v[24:25], v41, off
	s_mov_b64 exec, -1
	v_lshl_add_u64 v[24:25], v[24:25], 0, v[26:27]
	s_add_i32 s99, s99, s6
	s_cmp_gt_i32 s99, s9
	s_cbranch_scc1 .Lp0c_done
	s_min_i32 s7, s98, s9
	s_cmp_lt_i32 s7, s8
	s_cselect_b32 s0, s52, s54
	s_cselect_b32 s1, s53, s55
	s_and_b32 s7, s7, 0x3fff
	s_lshl_b32 s7, s7, 12
	s_add_u32 s0, s0, s7
	s_addc_u32 s1, s1, 0
	global_load_dwordx4 v[78:81], v22, s[0:1] nt
	global_load_dwordx4 v[82:85], v22, s[0:1] offset:1024 nt
	global_load_dwordx4 v[86:89], v22, s[0:1] offset:2048 nt
	global_load_dwordx4 v[90:93], v22, s[0:1] offset:3072 nt
	s_add_i32 s98, s98, s6
.Lp0c_loop:
	s_waitcnt vmcnt(27)
	v_mul_f32_e32 v41, v3, v3
	v_mul_f32_e32 v42, v7, v7
	v_mul_f32_e32 v43, v11, v11
	v_mul_f32_e32 v76, v15, v15
	v_fmac_f32_e32 v41, v2, v2
	v_fmac_f32_e32 v42, v6, v6
	v_fmac_f32_e32 v43, v10, v10
	v_fmac_f32_e32 v76, v14, v14
	v_fmac_f32_e32 v41, v4, v4
	v_fmac_f32_e32 v42, v8, v8
	v_fmac_f32_e32 v43, v12, v12
	v_fmac_f32_e32 v76, v16, v16
	v_fmac_f32_e32 v41, v5, v5
	v_fmac_f32_e32 v42, v9, v9
	v_fmac_f32_e32 v43, v13, v13
	v_fmac_f32_e32 v76, v17, v17
	v_add_f32_e32 v41, v41, v42
	v_add_f32_e32 v41, v41, v43
	v_add_f32_e32 v41, v41, v76
	ds_bpermute_b32 v42, v32, v41
	v_cvt_pk_bf16_f32 v2, v2, v3
	v_cvt_pk_bf16_f32 v3, v4, v5
	global_store_dwordx2 v[28:29], v[2:3], off
	v_cvt_pk_bf16_f32 v6, v6, v7
	v_cvt_pk_bf16_f32 v7, v8, v9
	global_store_dwordx2 v[28:29], v[6:7], off offset:512
	v_cvt_pk_bf16_f32 v10, v10, v11
	v_cvt_pk_bf16_f32 v11, v12, v13
	global_store_dwordx2 v[28:29], v[10:11], off offset:1024
	v_cvt_pk_bf16_f32 v14, v14, v15
	v_cvt_pk_bf16_f32 v15, v16, v17
	global_store_dwordx2 v[28:29], v[14:15], off offset:1536
	v_lshl_add_u64 v[28:29], v[28:29], 0, v[30:31]
	s_waitcnt lgkmcnt(0)
	v_add_f32_e32 v41, v41, v42
	ds_bpermute_b32 v42, v33, v41
	s_waitcnt lgkmcnt(0)
	v_add_f32_e32 v41, v41, v42
	ds_bpermute_b32 v42, v34, v41
	s_waitcnt lgkmcnt(0)
	v_add_f32_e32 v41, v41, v42
	ds_bpermute_b32 v42, v35, v41
	s_waitcnt lgkmcnt(0)
	v_add_f32_e32 v41, v41, v42
	ds_bpermute_b32 v42, v36, v41
	s_waitcnt lgkmcnt(0)
	v_add_f32_e32 v41, v41, v42
	ds_bpermute_b32 v42, v37, v41
	s_waitcnt lgkmcnt(0)
	v_add_f32_e32 v41, v41, v42
	s_mov_b64 exec, 1
	global_store_dword v[24:25], v41, off
	s_mov_b64 exec, -1
	v_lshl_add_u64 v[24:25], v[24:25], 0, v[26:27]
	s_add_i32 s99, s99, s6
	s_cmp_gt_i32 s99, s9
	s_cbranch_scc1 .Lp0c_done
	s_min_i32 s7, s98, s9
	s_cmp_lt_i32 s7, s8
	s_cselect_b32 s0, s52, s54
	s_cselect_b32 s1, s53, s55
	s_and_b32 s7, s7, 0x3fff
	s_lshl_b32 s7, s7, 12
	s_add_u32 s0, s0, s7
	s_addc_u32 s1, s1, 0
	global_load_dwordx4 v[2:5], v22, s[0:1] nt
	global_load_dwordx4 v[6:9], v22, s[0:1] offset:1024 nt
	global_load_dwordx4 v[10:13], v22, s[0:1] offset:2048 nt
	global_load_dwordx4 v[14:17], v22, s[0:1] offset:3072 nt
	s_add_i32 s98, s98, s6
	s_waitcnt vmcnt(27)
	v_mul_f32_e32 v41, v45, v45
	v_mul_f32_e32 v42, v49, v49
	v_mul_f32_e32 v43, v53, v53
	v_mul_f32_e32 v76, v57, v57
	v_fmac_f32_e32 v41, v44, v44
	v_fmac_f32_e32 v42, v48, v48
	v_fmac_f32_e32 v43, v52, v52
	v_fmac_f32_e32 v76, v56, v56
	v_fmac_f32_e32 v41, v46, v46
	v_fmac_f32_e32 v42, v50, v50
	v_fmac_f32_e32 v43, v54, v54
	v_fmac_f32_e32 v76, v58, v58
	v_fmac_f32_e32 v41, v47, v47
	v_fmac_f32_e32 v42, v51, v51
	v_fmac_f32_e32 v43, v55, v55
	v_fmac_f32_e32 v76, v59, v59
	v_add_f32_e32 v41, v41, v42
	v_add_f32_e32 v41, v41, v43
	v_add_f32_e32 v41, v41, v76
	ds_bpermute_b32 v42, v32, v41
	v_cvt_pk_bf16_f32 v44, v44, v45
	v_cvt_pk_bf16_f32 v45, v46, v47
	global_store_dwordx2 v[28:29], v[44:45], off
	v_cvt_pk_bf16_f32 v48, v48, v49
	v_cvt_pk_bf16_f32 v49, v50, v51
	global_store_dwordx2 v[28:29], v[48:49], off offset:512
	v_cvt_pk_bf16_f32 v52, v52, v53
	v_cvt_pk_bf16_f32 v53, v54, v55
	global_store_dwordx2 v[28:29], v[52:53], off offset:1024
	v_cvt_pk_bf16_f32 v56, v56, v57
	v_cvt_pk_bf16_f32 v57, v58, v59
	global_store_dwordx2 v[28:29], v[56:57], off offset:1536
	v_lshl_add_u64 v[28:29], v[28:29], 0, v[30:31]
	s_waitcnt lgkmcnt(0)
	v_add_f32_e32 v41, v41, v42
	ds_bpermute_b32 v42, v33, v41
	s_waitcnt lgkmcnt(0)
	v_add_f32_e32 v41, v41, v42
	ds_bpermute_b32 v42, v34, v41
	s_waitcnt lgkmcnt(0)
	v_add_f32_e32 v41, v41, v42
	ds_bpermute_b32 v42, v35, v41
	s_waitcnt lgkmcnt(0)
	v_add_f32_e32 v41, v41, v42
	ds_bpermute_b32 v42, v36, v41
	s_waitcnt lgkmcnt(0)
	v_add_f32_e32 v41, v41, v42
	ds_bpermute_b32 v42, v37, v41
	s_waitcnt lgkmcnt(0)
	v_add_f32_e32 v41, v41, v42
	s_mov_b64 exec, 1
	global_store_dword v[24:25], v41, off
	s_mov_b64 exec, -1
	v_lshl_add_u64 v[24:25], v[24:25], 0, v[26:27]
	s_add_i32 s99, s99, s6
	s_cmp_gt_i32 s99, s9
	s_cbranch_scc1 .Lp0c_done
	s_min_i32 s7, s98, s9
	s_cmp_lt_i32 s7, s8
	s_cselect_b32 s0, s52, s54
	s_cselect_b32 s1, s53, s55
	s_and_b32 s7, s7, 0x3fff
	s_lshl_b32 s7, s7, 12
	s_add_u32 s0, s0, s7
	s_addc_u32 s1, s1, 0
	global_load_dwordx4 v[44:47], v22, s[0:1] nt
	global_load_dwordx4 v[48:51], v22, s[0:1] offset:1024 nt
	global_load_dwordx4 v[52:55], v22, s[0:1] offset:2048 nt
	global_load_dwordx4 v[56:59], v22, s[0:1] offset:3072 nt
	s_add_i32 s98, s98, s6
	s_waitcnt vmcnt(27)
	v_mul_f32_e32 v41, v61, v61
	v_mul_f32_e32 v42, v65, v65
	v_mul_f32_e32 v43, v69, v69
	v_mul_f32_e32 v76, v73, v73
	v_fmac_f32_e32 v41, v60, v60
	v_fmac_f32_e32 v42, v64, v64
	v_fmac_f32_e32 v43, v68, v68
	v_fmac_f32_e32 v76, v72, v72
	v_fmac_f32_e32 v41, v62, v62
	v_fmac_f32_e32 v42, v66, v66
	v_fmac_f32_e32 v43, v70, v70
	v_fmac_f32_e32 v76, v74, v74
	v_fmac_f32_e32 v41, v63, v63
	v_fmac_f32_e32 v42, v67, v67
	v_fmac_f32_e32 v43, v71, v71
	v_fmac_f32_e32 v76, v75, v75
	v_add_f32_e32 v41, v41, v42
	v_add_f32_e32 v41, v41, v43
	v_add_f32_e32 v41, v41, v76
	ds_bpermute_b32 v42, v32, v41
	v_cvt_pk_bf16_f32 v60, v60, v61
	v_cvt_pk_bf16_f32 v61, v62, v63
	global_store_dwordx2 v[28:29], v[60:61], off
	v_cvt_pk_bf16_f32 v64, v64, v65
	v_cvt_pk_bf16_f32 v65, v66, v67
	global_store_dwordx2 v[28:29], v[64:65], off offset:512
	v_cvt_pk_bf16_f32 v68, v68, v69
	v_cvt_pk_bf16_f32 v69, v70, v71
	global_store_dwordx2 v[28:29], v[68:69], off offset:1024
	v_cvt_pk_bf16_f32 v72, v72, v73
	v_cvt_pk_bf16_f32 v73, v74, v75
	global_store_dwordx2 v[28:29], v[72:73], off offset:1536
	v_lshl_add_u64 v[28:29], v[28:29], 0, v[30:31]
	s_waitcnt lgkmcnt(0)
	v_add_f32_e32 v41, v41, v42
	ds_bpermute_b32 v42, v33, v41
	s_waitcnt lgkmcnt(0)
	v_add_f32_e32 v41, v41, v42
	ds_bpermute_b32 v42, v34, v41
	s_waitcnt lgkmcnt(0)
	v_add_f32_e32 v41, v41, v42
	ds_bpermute_b32 v42, v35, v41
	s_waitcnt lgkmcnt(0)
	v_add_f32_e32 v41, v41, v42
	ds_bpermute_b32 v42, v36, v41
	s_waitcnt lgkmcnt(0)
	v_add_f32_e32 v41, v41, v42
	ds_bpermute_b32 v42, v37, v41
	s_waitcnt lgkmcnt(0)
	v_add_f32_e32 v41, v41, v42
	s_mov_b64 exec, 1
	global_store_dword v[24:25], v41, off
	s_mov_b64 exec, -1
	v_lshl_add_u64 v[24:25], v[24:25], 0, v[26:27]
	s_add_i32 s99, s99, s6
	s_cmp_gt_i32 s99, s9
	s_cbranch_scc1 .Lp0c_done
	s_min_i32 s7, s98, s9
	s_cmp_lt_i32 s7, s8
	s_cselect_b32 s0, s52, s54
	s_cselect_b32 s1, s53, s55
	s_and_b32 s7, s7, 0x3fff
	s_lshl_b32 s7, s7, 12
	s_add_u32 s0, s0, s7
	s_addc_u32 s1, s1, 0
	global_load_dwordx4 v[60:63], v22, s[0:1] nt
	global_load_dwordx4 v[64:67], v22, s[0:1] offset:1024 nt
	global_load_dwordx4 v[68:71], v22, s[0:1] offset:2048 nt
	global_load_dwordx4 v[72:75], v22, s[0:1] offset:3072 nt
	s_add_i32 s98, s98, s6
	s_waitcnt vmcnt(27)
	v_mul_f32_e32 v41, v79, v79
	v_mul_f32_e32 v42, v83, v83
	v_mul_f32_e32 v43, v87, v87
	v_mul_f32_e32 v76, v91, v91
	v_fmac_f32_e32 v41, v78, v78
	v_fmac_f32_e32 v42, v82, v82
	v_fmac_f32_e32 v43, v86, v86
	v_fmac_f32_e32 v76, v90, v90
	v_fmac_f32_e32 v41, v80, v80
	v_fmac_f32_e32 v42, v84, v84
	v_fmac_f32_e32 v43, v88, v88
	v_fmac_f32_e32 v76, v92, v92
	v_fmac_f32_e32 v41, v81, v81
	v_fmac_f32_e32 v42, v85, v85
	v_fmac_f32_e32 v43, v89, v89
	v_fmac_f32_e32 v76, v93, v93
	v_add_f32_e32 v41, v41, v42
	v_add_f32_e32 v41, v41, v43
	v_add_f32_e32 v41, v41, v76
	ds_bpermute_b32 v42, v32, v41
	v_cvt_pk_bf16_f32 v78, v78, v79
	v_cvt_pk_bf16_f32 v79, v80, v81
	global_store_dwordx2 v[28:29], v[78:79], off
	v_cvt_pk_bf16_f32 v82, v82, v83
	v_cvt_pk_bf16_f32 v83, v84, v85
	global_store_dwordx2 v[28:29], v[82:83], off offset:512
	v_cvt_pk_bf16_f32 v86, v86, v87
	v_cvt_pk_bf16_f32 v87, v88, v89
	global_store_dwordx2 v[28:29], v[86:87], off offset:1024
	v_cvt_pk_bf16_f32 v90, v90, v91
	v_cvt_pk_bf16_f32 v91, v92, v93
	global_store_dwordx2 v[28:29], v[90:91], off offset:1536
	v_lshl_add_u64 v[28:29], v[28:29], 0, v[30:31]
	s_waitcnt lgkmcnt(0)
	v_add_f32_e32 v41, v41, v42
	ds_bpermute_b32 v42, v33, v41
	s_waitcnt lgkmcnt(0)
	v_add_f32_e32 v41, v41, v42
	ds_bpermute_b32 v42, v34, v41
	s_waitcnt lgkmcnt(0)
	v_add_f32_e32 v41, v41, v42
	ds_bpermute_b32 v42, v35, v41
	s_waitcnt lgkmcnt(0)
	v_add_f32_e32 v41, v41, v42
	ds_bpermute_b32 v42, v36, v41
	s_waitcnt lgkmcnt(0)
	v_add_f32_e32 v41, v41, v42
	ds_bpermute_b32 v42, v37, v41
	s_waitcnt lgkmcnt(0)
	v_add_f32_e32 v41, v41, v42
	s_mov_b64 exec, 1
	global_store_dword v[24:25], v41, off
	s_mov_b64 exec, -1
	v_lshl_add_u64 v[24:25], v[24:25], 0, v[26:27]
	s_add_i32 s99, s99, s6
	s_cmp_gt_i32 s99, s9
	s_cbranch_scc1 .Lp0c_done
	s_min_i32 s7, s98, s9
	s_cmp_lt_i32 s7, s8
	s_cselect_b32 s0, s52, s54
	s_cselect_b32 s1, s53, s55
	s_and_b32 s7, s7, 0x3fff
	s_lshl_b32 s7, s7, 12
	s_add_u32 s0, s0, s7
	s_addc_u32 s1, s1, 0
	global_load_dwordx4 v[78:81], v22, s[0:1] nt
	global_load_dwordx4 v[82:85], v22, s[0:1] offset:1024 nt
	global_load_dwordx4 v[86:89], v22, s[0:1] offset:2048 nt
	global_load_dwordx4 v[90:93], v22, s[0:1] offset:3072 nt
	s_add_i32 s98, s98, s6
	s_branch .Lp0c_loop
.Lp0c_done:
.LBB0_125:
	s_or_b64 exec, exec, s[4:5]
	s_waitcnt vmcnt(0)
	s_waitcnt lgkmcnt(0)
	s_barrier
	s_mov_b64 s[0:1], exec
	v_readlane_b32 s4, v255, 0
	v_readlane_b32 s5, v255, 1
	s_and_b64 s[4:5], s[0:1], s[4:5]
	s_mov_b64 exec, s[4:5]
	s_cbranch_execz .LBB0_177
	s_add_i32 s4, 0, 0x24c00
	v_mov_b32_e32 v1, s4
	s_waitcnt vmcnt(0) expcnt(0) lgkmcnt(0)
	ds_read_b32 v3, v1
	s_add_i32 s4, 0, 0x24c04
	v_mov_b32_e32 v1, s4
	ds_read_b32 v1, v1
	s_waitcnt lgkmcnt(1)
	v_cmp_ne_u32_e32 vcc, 0, v3
	s_cbranch_vccnz .LBB0_141
	v_readlane_b32 s4, v255, 35
	v_readlane_b32 s5, v255, 36
	s_load_dwordx2 s[8:9], s[4:5], 0x4
	s_add_u32 s4, s78, 0xfffc200
	s_addc_u32 s5, s79, 0
	s_add_u32 s6, s78, 0xfffc400
	s_addc_u32 s7, s79, 0
	s_waitcnt lgkmcnt(0)
	s_mul_i32 s14, s8, s33
	s_add_u32 s8, s78, 0xfffc500
	s_mul_i32 s14, s14, s9
	s_addc_u32 s9, s79, 0
	s_add_u32 s16, s78, 0xfffc600
	s_addc_u32 s17, s79, 0
	s_add_u32 s20, s78, 0xfffc700
	s_addc_u32 s21, s79, 0
	s_add_u32 s22, s78, 0xfffc800
	s_addc_u32 s23, s79, 0
	s_add_u32 s24, s78, 0xfffc900
	s_addc_u32 s25, s79, 0
	s_add_u32 s30, s78, 0xfffca00
	s_addc_u32 s31, s79, 0
	s_add_u32 s34, s78, 0xfffcb00
	s_addc_u32 s35, s79, 0
	s_add_u32 s36, s78, 0xfffcc00
	s_addc_u32 s37, s79, 0
	s_add_u32 s38, s78, 0xfffcd00
	s_addc_u32 s39, s79, 0
	s_add_u32 s40, s78, 0xfffce00
	s_addc_u32 s41, s79, 0
	s_add_u32 s42, s78, 0xfffcf00
	s_addc_u32 s43, s79, 0
	s_add_u32 s44, s78, 0xfffd000
	s_addc_u32 s45, s79, 0
	s_add_u32 s46, s78, 0xfffd100
	s_addc_u32 s47, s79, 0
	s_add_u32 s52, s78, 0xfffd200
	s_addc_u32 s53, s79, 0
	s_add_u32 s54, s78, 0xfffd300
	s_addc_u32 s55, s79, 0
	s_mov_b32 s15, 1
	v_mov_b32_e32 v17, 0
	s_branch .LBB0_129
